# base7 + nt on HGRN scan loads, scan output stores, FFT input loads
# baseline (speedup 1.0000x reference)
; __device__ __forceinline__ void phase_scan_chunk(const Args& a, LAS unsigned char* lds, const WCtx& w, int l) {
;     ...
;             GLA_LOAD(0);
.LBB0_1431:
	s_bfe_u32 s22, s23, 0x40002
	s_lshl_b32 s2, s23, 6
	s_and_b32 s27, s2, 0xc0
	s_lshl_b32 s26, s22, 8
	v_readlane_b32 s2, v253, 41
	s_bitset1_b32 s26, 15
	v_readlane_b32 s3, v253, 42
	v_or_b32_e32 v4, s26, v114
	s_mov_b32 s15, s5
	v_mov_b64_e32 v[2:3], s[2:3]
	v_mad_u64_u32 v[2:3], s[2:3], v4, s4, v[2:3]
	s_lshl_b32 s14, s27, 1
	v_lshl_add_u64 v[2:3], v[2:3], 0, s[14:15]
	s_waitcnt vmcnt(0)
	v_lshlrev_b32_e32 v50, 1, v116
	v_lshl_add_u64 v[2:3], v[2:3], 0, v[50:51]
	v_lshl_add_u64 v[6:7], v[2:3], 0, v[42:43]
	v_lshl_add_u64 v[8:9], v[6:7], 0, v[42:43]
	v_lshl_add_u64 v[10:11], v[8:9], 0, v[42:43]
	v_lshl_add_u64 v[12:13], v[10:11], 0, v[42:43]
	v_lshl_add_u64 v[14:15], v[12:13], 0, v[42:43]
	v_lshl_add_u64 v[16:17], v[14:15], 0, v[42:43]
	v_lshl_add_u64 v[18:19], v[16:17], 0, v[42:43]
	v_lshl_add_u64 v[20:21], v[18:19], 0, v[42:43]
	v_lshl_add_u64 v[22:23], v[20:21], 0, v[42:43]
	s_waitcnt vmcnt(0)
	v_lshl_add_u64 v[24:25], v[22:23], 0, v[42:43]
	v_lshl_add_u64 v[26:27], v[24:25], 0, v[42:43]
	v_lshl_add_u64 v[28:29], v[26:27], 0, v[42:43]
	s_movk_i32 s2, 0xc00
	v_lshl_add_u64 v[30:31], v[28:29], 0, v[42:43]
	v_mad_u64_u32 v[4:5], s[2:3], v4, s2, v[40:41]
	v_lshl_add_u64 v[32:33], v[30:31], 0, v[42:43]
	s_lshl_b32 s2, s27, 2
	s_mov_b32 s3, s5
	v_lshl_add_u64 v[34:35], v[32:33], 0, v[42:43]
	v_lshl_add_u64 v[4:5], v[4:5], 0, s[2:3]
	global_load_ushort v170, v[2:3], off nt
	global_load_ushort v171, v[6:7], off nt
	global_load_ushort v172, v[8:9], off nt
	global_load_ushort v173, v[10:11], off nt
	global_load_ushort v174, v[12:13], off nt
	global_load_ushort v175, v[14:15], off nt
	global_load_ushort v176, v[16:17], off nt
	global_load_ushort v177, v[18:19], off nt
	global_load_ushort v178, v[20:21], off nt
	global_load_ushort v179, v[22:23], off nt
	global_load_ushort v180, v[24:25], off nt
	global_load_ushort v181, v[26:27], off nt
	global_load_ushort v182, v[28:29], off nt
	global_load_ushort v183, v[30:31], off nt
	global_load_ushort v184, v[32:33], off nt
	global_load_ushort v185, v[34:35], off nt
	v_lshlrev_b32_e32 v50, 2, v116
	global_load_ushort v186, v[2:3], off offset:512 nt
	global_load_ushort v187, v[6:7], off offset:512 nt
	global_load_ushort v188, v[8:9], off offset:512 nt
	global_load_ushort v189, v[10:11], off offset:512 nt
	global_load_ushort v190, v[12:13], off offset:512 nt
	global_load_ushort v191, v[14:15], off offset:512 nt
	global_load_ushort v192, v[16:17], off offset:512 nt
	global_load_ushort v193, v[18:19], off offset:512 nt
	global_load_ushort v194, v[20:21], off offset:512 nt
	global_load_ushort v195, v[22:23], off offset:512 nt
	global_load_ushort v197, v[24:25], off offset:512 nt
	global_load_ushort v199, v[26:27], off offset:512 nt
	global_load_ushort v200, v[28:29], off offset:512 nt
	global_load_ushort v201, v[30:31], off offset:512 nt
	global_load_ushort v202, v[32:33], off offset:512 nt
	global_load_ushort v203, v[34:35], off offset:512 nt
	v_lshl_add_u64 v[2:3], v[4:5], 0, v[50:51]
	v_lshl_add_u64 v[4:5], v[2:3], 0, v[44:45]
	v_lshl_add_u64 v[6:7], v[4:5], 0, v[44:45]
	v_lshl_add_u64 v[8:9], v[6:7], 0, v[44:45]
	v_lshl_add_u64 v[10:11], v[8:9], 0, v[44:45]
	global_load_dword v50, v[2:3], off nt
	global_load_dword v204, v[4:5], off nt
	global_load_dword v205, v[6:7], off nt
	global_load_dword v206, v[8:9], off nt
	global_load_dword v207, v[10:11], off nt
	v_lshl_add_u64 v[2:3], v[10:11], 0, v[44:45]
	global_load_dword v208, v[2:3], off nt
	v_lshl_add_u64 v[2:3], v[2:3], 0, v[44:45]
	global_load_dword v209, v[2:3], off nt
	v_lshl_add_u64 v[2:3], v[2:3], 0, v[44:45]
	global_load_dword v210, v[2:3], off nt
	v_lshl_add_u64 v[2:3], v[2:3], 0, v[44:45]
	global_load_dword v211, v[2:3], off nt
	v_lshl_add_u64 v[2:3], v[2:3], 0, v[44:45]
	global_load_dword v212, v[2:3], off nt
	v_lshl_add_u64 v[2:3], v[2:3], 0, v[44:45]
	global_load_dword v213, v[2:3], off nt
	v_lshl_add_u64 v[2:3], v[2:3], 0, v[44:45]
	global_load_dword v214, v[2:3], off nt
	v_lshl_add_u64 v[2:3], v[2:3], 0, v[44:45]
	global_load_dword v215, v[2:3], off nt
	v_lshl_add_u64 v[2:3], v[2:3], 0, v[44:45]
	global_load_dword v216, v[2:3], off nt
	v_lshl_add_u64 v[2:3], v[2:3], 0, v[44:45]
	global_load_dword v217, v[2:3], off nt
	v_lshl_add_u64 v[2:3], v[2:3], 0, v[44:45]
	global_load_dword v218, v[2:3], off nt
	v_mov_b32_e32 v64, 0
	v_lshl_add_u64 v[58:59], v[38:39], 0, s[14:15]
	v_lshl_add_u64 v[60:61], v[46:47], 0, s[14:15]
	v_lshl_add_u64 v[62:63], v[48:49], 0, s[2:3]
	s_lshl_b32 s27, s22, 11
	s_mov_b32 s28, 0
	s_mov_b32 s29, 0
	s_mov_b32 s30, 0
	v_mov_b32_e32 v65, v64
	v_mov_b32_e32 v66, v64
	v_mov_b32_e32 v67, v64
	v_mov_b32_e32 v68, v64
	v_mov_b32_e32 v69, v64
	v_mov_b32_e32 v70, v64
	v_mov_b32_e32 v71, v64
	v_mov_b32_e32 v72, v64
	v_mov_b32_e32 v73, v64
	v_mov_b32_e32 v74, v64
	v_mov_b32_e32 v75, v64
	v_mov_b32_e32 v76, v64
	v_mov_b32_e32 v77, v64
	v_mov_b32_e32 v78, v64
	v_mov_b32_e32 v79, v64
	s_branch .LBB0_1433

; __device__ __forceinline__ void phase_scan_chunk(const Args& a, LAS unsigned char* lds, const WCtx& w, int l) {
;     ...
;                 if (c + 1 < 36) GLA_LOAD(c + 1);
.LBB0_1504:
	v_mad_i64_i32 v[4:5], s[2:3], v2, s4, v[60:61]
	v_lshl_add_u64 v[6:7], v[4:5], 0, v[42:43]
	v_lshl_add_u64 v[8:9], v[6:7], 0, v[42:43]
	v_lshl_add_u64 v[10:11], v[8:9], 0, v[42:43]
	v_lshl_add_u64 v[12:13], v[10:11], 0, v[42:43]
	v_lshl_add_u64 v[14:15], v[12:13], 0, v[42:43]
	v_lshl_add_u64 v[16:17], v[14:15], 0, v[42:43]
	v_lshl_add_u64 v[18:19], v[16:17], 0, v[42:43]
	v_lshl_add_u64 v[20:21], v[18:19], 0, v[42:43]
	v_lshl_add_u64 v[22:23], v[20:21], 0, v[42:43]
	v_lshl_add_u64 v[24:25], v[22:23], 0, v[42:43]
	v_lshl_add_u64 v[26:27], v[24:25], 0, v[42:43]
	v_lshl_add_u64 v[28:29], v[26:27], 0, v[42:43]
	v_lshl_add_u64 v[30:31], v[28:29], 0, v[42:43]
	v_lshl_add_u64 v[32:33], v[30:31], 0, v[42:43]
	v_lshl_add_u64 v[34:35], v[32:33], 0, v[42:43]
	s_movk_i32 s2, 0xc00
	global_load_ushort v170, v[4:5], off nt
	global_load_ushort v171, v[6:7], off nt
	global_load_ushort v172, v[8:9], off nt
	global_load_ushort v173, v[10:11], off nt
	global_load_ushort v174, v[12:13], off nt
	global_load_ushort v175, v[14:15], off nt
	global_load_ushort v176, v[16:17], off nt
	global_load_ushort v177, v[18:19], off nt
	global_load_ushort v178, v[20:21], off nt
	global_load_ushort v179, v[22:23], off nt
	global_load_ushort v180, v[24:25], off nt
	global_load_ushort v181, v[26:27], off nt
	global_load_ushort v182, v[28:29], off nt
	global_load_ushort v183, v[30:31], off nt
	global_load_ushort v184, v[32:33], off nt
	global_load_ushort v185, v[34:35], off nt
	v_mad_i64_i32 v[2:3], s[2:3], v2, s2, v[62:63]
	global_load_ushort v186, v[4:5], off offset:512 nt
	global_load_ushort v187, v[6:7], off offset:512 nt
	global_load_ushort v188, v[8:9], off offset:512 nt
	global_load_ushort v189, v[10:11], off offset:512 nt
	global_load_ushort v190, v[12:13], off offset:512 nt
	global_load_ushort v191, v[14:15], off offset:512 nt
	global_load_ushort v192, v[16:17], off offset:512 nt
	global_load_ushort v193, v[18:19], off offset:512 nt
	global_load_ushort v194, v[20:21], off offset:512 nt
	global_load_ushort v195, v[22:23], off offset:512 nt
	global_load_ushort v197, v[24:25], off offset:512 nt
	global_load_ushort v199, v[26:27], off offset:512 nt
	global_load_ushort v200, v[28:29], off offset:512 nt
	global_load_ushort v201, v[30:31], off offset:512 nt
	global_load_ushort v202, v[32:33], off offset:512 nt
	global_load_ushort v203, v[34:35], off offset:512 nt
	v_lshl_add_u64 v[4:5], v[2:3], 0, v[44:45]
	v_lshl_add_u64 v[6:7], v[4:5], 0, v[44:45]
	v_lshl_add_u64 v[8:9], v[6:7], 0, v[44:45]
	v_lshl_add_u64 v[10:11], v[8:9], 0, v[44:45]
	global_load_dword v50, v[2:3], off nt
	global_load_dword v204, v[4:5], off nt
	global_load_dword v205, v[6:7], off nt
	global_load_dword v206, v[8:9], off nt
	global_load_dword v207, v[10:11], off nt
	v_lshl_add_u64 v[2:3], v[10:11], 0, v[44:45]
	global_load_dword v208, v[2:3], off nt
	v_lshl_add_u64 v[2:3], v[2:3], 0, v[44:45]
	global_load_dword v209, v[2:3], off nt
	v_lshl_add_u64 v[2:3], v[2:3], 0, v[44:45]
	global_load_dword v210, v[2:3], off nt
	v_lshl_add_u64 v[2:3], v[2:3], 0, v[44:45]
	global_load_dword v211, v[2:3], off nt
	v_lshl_add_u64 v[2:3], v[2:3], 0, v[44:45]
	global_load_dword v212, v[2:3], off nt
	v_lshl_add_u64 v[2:3], v[2:3], 0, v[44:45]
	global_load_dword v213, v[2:3], off nt
	v_lshl_add_u64 v[2:3], v[2:3], 0, v[44:45]
	global_load_dword v214, v[2:3], off nt
	v_lshl_add_u64 v[2:3], v[2:3], 0, v[44:45]
	global_load_dword v215, v[2:3], off nt
	v_lshl_add_u64 v[2:3], v[2:3], 0, v[44:45]
	global_load_dword v216, v[2:3], off nt
	v_lshl_add_u64 v[2:3], v[2:3], 0, v[44:45]
	global_load_dword v217, v[2:3], off nt
	v_lshl_add_u64 v[2:3], v[2:3], 0, v[44:45]
	global_load_dword v218, v[2:3], off nt
